# v_combo17 + one static s_setprio 1 for scan waves 0-3 (they also stage the value slice and factors), reset after the loop
# baseline (speedup 1.0000x reference)
.LBB0_618:
	v_add_u32_e32 v245, v156, v155
	s_waitcnt vmcnt(0)
	s_and_b64 vcc, exec, s[6:7]
	s_cbranch_scc0 .Lmy_scan_prio_done
	s_setprio 1
.Lmy_scan_prio_done:
.Lscan_head:
	s_add_i32 s57, s57, 4
	ds_read_b128 v[96:99], v154 offset:39936
	ds_read_b128 v[200:203], v178
	ds_read_b128 v[204:207], v178 offset:64
	ds_read_b128 v[208:211], v178 offset:128
	ds_read_b128 v[212:215], v178 offset:192
	ds_read_b128 v[216:219], v174 offset:17408
	ds_read_b128 v[184:187], v175 offset:17408
	ds_read_b128 v[220:223], v174 offset:17472
	ds_read_b128 v[188:191], v175 offset:17472
	ds_read_b128 v[224:227], v174 offset:17536
	ds_read_b128 v[192:195], v175 offset:17536
	ds_read_b128 v[228:231], v174 offset:17600
	ds_read_b128 v[196:199], v175 offset:17600
	s_min_u32 s14, s57, 0x7a
	s_add_i32 s22, s14, 5
	s_lshl_b32 s14, s14, 6
	s_sub_i32 s44, 0x1e80, s14
	s_lshl_b32 s45, s22, 6
	s_and_b64 s[14:15], s[74:75], exec
	s_cselect_b32 s14, s45, s44
	s_ashr_i32 s15, s14, 31
	s_lshl_b64 s[14:15], s[14:15], 10
	s_add_u32 s14, s14, s56
	s_addc_u32 s15, s15, 0
	s_lshl_b64 s[14:15], s[14:15], 1
	s_mulk_i32 s22, 0x600
	s_waitcnt lgkmcnt(12)
	v_pk_mul_f32 v[108:109], v[140:141], v[96:97]
	v_pk_mul_f32 v[110:111], v[146:147], v[98:99]
	v_pk_mul_f32 v[112:113], v[144:145], v[96:97]
	v_pk_mul_f32 v[114:115], v[142:143], v[98:99]
	v_cvt_pk_bf16_f32 v108, v108, v109
	v_cvt_pk_bf16_f32 v109, v110, v111
	v_cvt_pk_bf16_f32 v112, v112, v113
	v_cvt_pk_bf16_f32 v113, v114, v115
	ds_write_b64 v177, v[108:109]
	ds_write_b64 v177, v[112:113] offset:4352
	s_waitcnt lgkmcnt(8)
	v_mfma_f32_16x16x32_bf16 v[100:103], v[216:219], v[200:203], 0
	v_mfma_f32_16x16x32_bf16 v[104:107], v[184:187], v[200:203], 0
	s_waitcnt lgkmcnt(6)
	v_mfma_f32_16x16x32_bf16 v[100:103], v[220:223], v[204:207], v[100:103]
	v_mfma_f32_16x16x32_bf16 v[104:107], v[188:191], v[204:207], v[104:107]
	s_waitcnt lgkmcnt(4)
	v_mfma_f32_16x16x32_bf16 v[100:103], v[224:227], v[208:211], v[100:103]
	v_mfma_f32_16x16x32_bf16 v[104:107], v[192:195], v[208:211], v[104:107]
	s_waitcnt lgkmcnt(2)
	v_mfma_f32_16x16x32_bf16 v[100:103], v[228:231], v[212:215], v[100:103]
	v_mfma_f32_16x16x32_bf16 v[104:107], v[196:199], v[212:215], v[104:107]
	s_waitcnt vmcnt(16)
	ds_write_b128 v148, v[0:3] offset:41472
	ds_write_b128 v148, v[4:7] offset:50176
	ds_write_b128 v148, v[8:11] offset:58880
	ds_write_b128 v153, v[16:19] offset:8704
	s_and_saveexec_b64 s[44:45], s[6:7]
	s_cbranch_execz .Lscan_novv_0
	ds_write_b128 v176, v[20:23]

.Lscan_vtj_3:
	ds_read_b128 v[240:243], v159
	s_waitcnt lgkmcnt(2)
	v_mfma_f32_16x16x32_bf16 v[200:203], v[108:111], v[184:187], 0
	v_mfma_f32_16x16x32_bf16 v[204:207], v[108:111], v[188:191], 0
	v_mfma_f32_16x16x32_bf16 v[200:203], v[112:115], v[192:195], v[200:203]
	v_mfma_f32_16x16x32_bf16 v[204:207], v[112:115], v[196:199], v[204:207]
	v_lshl_add_u64 v[216:217], s[44:45], 0, v[126:127]
	v_lshlrev_b64 v[216:217], 11, v[216:217]
	v_lshl_add_u64 v[216:217], v[134:135], 0, v[216:217]
	s_nop 0
	v_cvt_pk_bf16_f32 v100, v104, v105
	v_cvt_pk_bf16_f32 v101, v106, v107
	global_store_dwordx2 v[216:217], v[100:101], off
	s_waitcnt lgkmcnt(0)
	s_nop 1
	v_pk_mul_f32 v[208:209], v[240:241], v[200:201]
	v_pk_mul_f32 v[210:211], v[242:243], v[202:203]
	v_pk_mul_f32 v[212:213], v[240:241], v[204:205]
	v_pk_mul_f32 v[214:215], v[242:243], v[206:207]
	v_pk_fma_f32 v[140:141], v[140:141], v[96:97], v[208:209]
	v_pk_fma_f32 v[146:147], v[146:147], v[98:99], v[210:211]
	v_pk_fma_f32 v[144:145], v[144:145], v[96:97], v[212:213]
	v_pk_fma_f32 v[142:143], v[142:143], v[98:99], v[214:215]
	s_barrier
	s_addk_i32 s58, 0x100
	s_addk_i32 s59, 0xff00
	s_cmpk_gt_u32 s57, 0x7b
	s_cbranch_scc0 .Lscan_head
	s_setprio 0
	s_branch .LBB0_609
